# attention phase: static s_setprio 1 raise given to waves 0-3 instead of waves 4-7 (A/B of which half benefits)
# speedup vs baseline: 1.0083x; 1.0083x over previous
; __device__ __forceinline__ void attn_phase(const Params& p, unsigned char* ws, int layer, LAS unsigned char* lds, const int tid, int rep) {
;     const int wid = __builtin_amdgcn_readfirstlane(tid >> 6);
;     const bf16_t* qkv = (const bf16_t*)(ws + WS_QKV);
;     const float* kmean = (const float*)(ws + WS_KMEAN);
;     bf16_t* outA = (bf16_t*)(ws + WS_ATTA); bf16_t* outB = (bf16_t*)(ws + WS_ATTB); bf16_t* outC = (bf16_t*)(ws + WS_ATTC);
;     if (wid >= 4) __builtin_amdgcn_s_setprio(1);
;     const bool a_static = (gridDim.x == 256);
.LBB0_388:
	s_andn2_b64 vcc, exec, s[0:1]
	s_cbranch_vccnz .LBB0_625
	v_readfirstlane_b32 s6, v236
	s_ashr_i32 s77, s6, 6
	s_cmp_lt_i32 s77, 4
	s_cselect_b64 s[0:1], -1, 0
	v_writelane_b32 v255, s0, 52
	s_and_b64 vcc, exec, s[0:1]
	s_nop 0
	v_writelane_b32 v255, s1, 53
	s_cbranch_vccz .LBB0_391
	s_setprio 1
